# projection-phase epilogue also reuses cached per-row rstd and row sums across the units of a workgroup
# speedup vs baseline: 1.0224x; 1.0074x over previous
; template <class Epi, class Sched, bool ALIGN_EPI = false, bool SP2 = false>
; __device__ __forceinline__ void gemm_phase(PG8_LAS unsigned char* lds, const Gemm g, const Sched& S, const Epi& E) {
;     ...
;     const int tid = tid_o, wid = __builtin_amdgcn_readfirstlane(tid >> 6), lane = tid & 63, wr = wid >> 2, wc = wid & 3, fr = lane & 15, fq = lane >> 4;
;     const int K = g.K, nt = K / BK;
;     unsigned voffA[2], voffB[2];
; #pragma unroll
;     for (int i = 0; i < 2; ++i) { int R, C; stage_rc(tid * 16 + i * 8192, R, C); const int Rb = Epi::PERM ? ((R & ~31) + perm32(R & 31)) : R;
;         voffA[i] = (unsigned)(R * K + C) * 2u; voffB[i] = (unsigned)(Rb * K + C) * 2u; }
;     const size_t kstep = (size_t)(BK * 2);
;     const size_t hstep = (size_t)HALF * K * 2;
;     const size_t tstep = 2 * hstep;
;     const unsigned ldsw = (unsigned)wid * 1024u;
;     const int aoff = lds_byte(wr * 64 + fr, fq * 8), boff = lds_byte(wc * 32 + fr, fq * 8);
;     ...
;     Unit cur, nxt; int ui = 0;
;     if (!S.next(0, cur)) return;
;     f32x4 acc[2][2][4][2];
; #pragma unroll
;     for (int a = 0; a < 2; ++a)
; #pragma unroll
;         for (int b = 0; b < 2; ++b)
; #pragma unroll
;             for (int m = 0; m < 4; ++m)
; #pragma unroll
;                 for (int n = 0; n < 2; ++n) acc[a][b][m][n] = (f32x4){0.f, 0.f, 0.f, 0.f};
;     bf16x8 At[4][2], B0[2][2], B1[2][2];
;     const char* cA = (const char*)g.A + (size_t)cur.pm * tstep; const char* cB = (const char*)g.Bt + (size_t)cur.pn * tstep;
;     S.a_ready(cur);
;     if constexpr (SP2) {
;         PG8_STAGE(PG8_SB(0, 0), cB, voffB); PG8_STAGE(PG8_SB(0, 1), cB + hstep, voffB); PG8_STAGE(PG8_SA(0, 0), cA, voffA); PG8_STAGE(PG8_SA(0, 1), cA + hstep, voffA);
;         if (wr == 1) PG8_BAR;
;         PG8_WAIT_V(2); PG8_BAR;
;         PG8_STAGE(PG8_SB(1, 0), cB + kstep, voffB); PG8_STAGE(PG8_SA(1, 0), cA + kstep, voffA); PG8_STAGE(PG8_SB(1, 1), cB + hstep + kstep, voffB);
;         PG8_WAIT_V(6); PG8_BAR;
;     } else {
;         PG8_STAGE(PG8_SB(0, 0), cB, voffB); PG8_STAGE(PG8_SA(0, 0), cA, voffA); PG8_STAGE(PG8_SB(0, 1), cB + hstep, voffB); PG8_STAGE(PG8_SA(0, 1), cA + hstep, voffA);
;         if (wr == 1) PG8_BAR;
;         PG8_WAIT_V(4); PG8_BAR;
;         PG8_STAGE(PG8_SB(1, 0), cB + kstep, voffB); PG8_STAGE(PG8_SA(1, 0), cA + kstep, voffA); PG8_STAGE(PG8_SB(1, 1), cB + hstep + kstep, voffB);
;         PG8_WAIT_V(6); PG8_BAR;
.LBB0_393:
	v_lshrrev_b32_e32 v16, 1, v14
	v_and_b32_e32 v16, 24, v16
	s_lshl_b32 s6, s6, 5
	s_mov_b64 s[44:45], 0x80
	v_and_b32_e32 v15, 15, v14
	v_lshlrev_b32_e32 v17, 1, v16
	v_lshlrev_b32_e32 v14, 2, v14
	s_and_b32 s12, s6, 0x60
	s_add_i32 m0, s14, 0x18000
	v_lshl_add_u64 v[6:7], v[6:7], 0, s[44:45]
	v_lshl_or_b32 v17, v15, 6, v17
	s_lshl_b32 s7, s8, 13
	v_and_b32_e32 v14, 32, v14
	s_lshl_b32 s6, s12, 7
	s_waitcnt vmcnt(2)
	s_barrier
	global_load_lds_dwordx4 v[6:7], off
	v_lshl_add_u64 v[4:5], v[4:5], 0, s[44:45]
	s_add_i32 m0, s14, 0x1a000
	s_add_i32 s68, s14, 0x8000
	s_add_i32 s69, s14, 0xa000
	v_bitop3_b32 v177, v17, s6, v14 bitop3:0xde
	global_load_lds_dwordx4 v[4:5], off
	v_lshl_add_u64 v[0:1], v[0:1], 0, s[44:45]
	s_mov_b32 m0, s68
	s_add_u32 s6, s96, 0x80080
	v_bitop3_b32 v18, v17, s7, v14 bitop3:0xde
	global_load_lds_dwordx4 v[0:1], off
	v_lshl_add_u64 v[0:1], v[2:3], 0, s[44:45]
	s_mov_b32 m0, s69
	s_addc_u32 s7, s97, 0
	global_load_lds_dwordx4 v[0:1], off
	s_add_i32 m0, s14, 0x1c000
	v_lshl_add_u64 v[0:1], s[6:7], 0, v[138:139]
	global_load_lds_dwordx4 v[0:1], off
	v_lshl_add_u64 v[0:1], s[6:7], 0, v[142:143]
	s_add_i32 m0, s14, 0x1e000
	s_cmpk_lt_u32 s9, 0x100
	global_load_lds_dwordx4 v[0:1], off
	v_lshlrev_b32_e32 v0, 2, v16
	v_mov_b32_e32 v1, v139
	v_lshl_add_u64 v[144:145], s[42:43], 0, v[0:1]
	v_lshlrev_b32_e32 v0, 15, v8
	v_and_b32_e32 v0, 0xffff0000, v0
	v_lshl_add_u32 v0, v9, 12, v0
	v_and_b32_e32 v1, 1, v8
	v_lshl_or_b32 v0, v1, 6, v0
	s_cselect_b64 s[86:87], -1, 0
	s_ashr_i32 s9, s8, 31
	v_lshl_add_u32 v146, v10, 1, v0
	v_lshlrev_b32_e32 v0, 15, v11
	v_lshl_or_b32 v176, s8, 6, v15
	s_lshl_b64 s[8:9], s[8:9], 12
	v_and_b32_e32 v0, 0xffff0000, v0
	s_waitcnt vmcnt(6)
	s_add_u32 s70, s72, s8
	v_lshl_add_u32 v0, v12, 12, v0
	v_and_b32_e32 v1, 1, v11
	s_addc_u32 s71, s22, s9
	v_lshl_or_b32 v0, v1, 6, v0
	s_add_i32 s80, 0, 0x10000
	s_add_i32 s81, 0, 0x14000
	v_cmp_eq_u32_e64 s[6:7], 0, v15
	v_or_b32_e32 v178, s12, v16
	v_mov_b32_e32 v147, v139
	v_lshl_add_u32 v148, v13, 1, v0
	v_mov_b32_e32 v149, v139
	v_mov_b64_e32 v[150:151], 0x400
	v_mov_b64_e32 v[152:153], 0x3ff
	v_add_u32_e32 v179, s80, v177
	v_add_u32_e32 v180, s81, v177
	v_add_u32_e32 v181, 0, v18
	v_mbcnt_hi_u32_b32 v182, -1, v216
	v_mov_b32_e32 v183, 0x358637bd
	v_mov_b32_e32 v184, 0x3e0293ee
	v_mov_b32_e32 v185, 0x3e38aa3b
	s_barrier
	s_mov_b32 s100, 0
	s_branch .LBB0_396

; __device__ __forceinline__ void rows_rstd(const float* ssq, int row0, int fq, float scale, float (&rs)[2][4]) {
;     f32x4 pa[2][4], pb[2][4];
; #pragma unroll
;     for (int ai = 0; ai < 2; ++ai)
; #pragma unroll
;         for (int m = 0; m < 4; ++m) { const f32x4* p = (const f32x4*)(ssq + (size_t)(row0 + ai * HALF + m * 16) * 32 + 8 * fq); pa[ai][m] = p[0]; pb[ai][m] = p[1]; }
; #pragma unroll
;     for (int ai = 0; ai < 2; ++ai)
; #pragma unroll
;         for (int m = 0; m < 4; ++m) { const f32x4 a = pa[ai][m], c = pb[ai][m]; float s = ((a[0] + a[1]) + (a[2] + a[3])) + ((c[0] + c[1]) + (c[2] + c[3]));
;             s += __shfl_xor(s, 16); s += __shfl_xor(s, 32); rs[ai][m] = __builtin_amdgcn_rsqf(s * (1.0f / DMODEL) + RMS_EPS) * scale; }
;     __device__ __forceinline__ void operator()(const f32x4 (&acc)[2][2][4][2], const Unit& u, int wr, int wc, int fr, int fq) const {
;         const int row0 = u.pm * BM + wr * 64 + fr, col0 = u.pn * BM + wc * 32 + 8 * fq;
;         const bool sig = u.pn >= 16; const float sc = u.pn < 4 ? qa_scale : ((u.pn >= 8 && u.pn < 12) ? qb_scale : 1.0f);
;         float rs[2][4];
;         rows_rstd(ssq, row0, fq, sc, rs);
.LBB0_406:
	s_cmp_lg_u32 s100, 0
	s_cbranch_scc1 .Lrc3_fast
	v_lshrrev_b32_e32 v251, 6, v222
	v_and_b32_e32 v250, 15, v222
	v_lshl_or_b32 v251, v251, 4, v250
	v_lshlrev_b32_e32 v251, 5, v251
	v_add_u32_e32 v251, 0x20000, v251
	v_lshl_add_u32 v170, s46, 8, v176
	v_ashrrev_i32_e32 v171, 31, v170
	v_lshlrev_b64 v[128:129], 7, v[170:171]
	v_lshl_add_u64 v[132:133], v[144:145], 0, v[128:129]
	global_load_dwordx4 v[128:131], v[132:133], off
	s_nop 0
	global_load_dwordx4 v[132:135], v[132:133], off offset:16
	v_or_b32_e32 v168, 16, v170
	v_ashrrev_i32_e32 v169, 31, v168
	v_lshlrev_b64 v[154:155], 7, v[168:169]
	v_or_b32_e32 v166, 32, v170
	v_lshl_add_u64 v[154:155], v[144:145], 0, v[154:155]
	v_ashrrev_i32_e32 v167, 31, v166
	global_load_dwordx4 v[172:175], v[154:155], off offset:16
	global_load_dwordx4 v[188:191], v[154:155], off
	v_lshlrev_b64 v[154:155], 7, v[166:167]
	v_lshl_add_u64 v[154:155], v[144:145], 0, v[154:155]
	global_load_dwordx4 v[192:195], v[154:155], off offset:16
	global_load_dwordx4 v[196:199], v[154:155], off
	v_or_b32_e32 v164, 48, v170
	v_ashrrev_i32_e32 v165, 31, v164
	v_lshlrev_b64 v[154:155], 7, v[164:165]
	v_add_u32_e32 v162, 0x80, v170
	v_lshl_add_u64 v[154:155], v[144:145], 0, v[154:155]
	v_ashrrev_i32_e32 v163, 31, v162
	global_load_dwordx4 v[200:203], v[154:155], off
	global_load_dwordx4 v[204:207], v[154:155], off offset:16
	v_lshlrev_b64 v[154:155], 7, v[162:163]
	v_lshl_add_u64 v[154:155], v[144:145], 0, v[154:155]
	global_load_dwordx4 v[208:211], v[154:155], off offset:16
	global_load_dwordx4 v[212:215], v[154:155], off
	v_add_u32_e32 v160, 0x90, v170
	v_and_b32_e32 v154, 64, v182
	v_ashrrev_i32_e32 v161, 31, v160
	v_add_u32_e32 v158, 0xa0, v170
	v_add_u32_e32 v186, 64, v154
	v_lshlrev_b64 v[154:155], 7, v[160:161]
	v_lshl_add_u64 v[154:155], v[144:145], 0, v[154:155]
	v_ashrrev_i32_e32 v159, 31, v158
	v_add_u32_e32 v156, 0xb0, v170
	global_load_dwordx4 v[218:221], v[154:155], off offset:16
	global_load_dwordx4 v[224:227], v[154:155], off
	v_lshlrev_b64 v[154:155], 7, v[158:159]
	v_ashrrev_i32_e32 v157, 31, v156
	v_lshl_add_u64 v[154:155], v[144:145], 0, v[154:155]
	global_load_dwordx4 v[228:231], v[154:155], off offset:16
	global_load_dwordx4 v[232:235], v[154:155], off
	v_lshlrev_b64 v[154:155], 7, v[156:157]
	v_lshl_add_u64 v[154:155], v[144:145], 0, v[154:155]
	global_load_dwordx4 v[236:239], v[154:155], off offset:16
	global_load_dwordx4 v[240:243], v[154:155], off
	s_cmp_lt_i32 s94, 16
	v_xor_b32_e32 v187, 16, v182
	v_xor_b32_e32 v217, 32, v182
	s_cselect_b64 s[96:97], -1, 0
	s_and_b32 s10, s94, 0x7ffffffc
	v_cmp_lt_i32_e32 vcc, v187, v186
	s_cmp_eq_u32 s10, 8
	s_mov_b64 s[10:11], -1
	v_cndmask_b32_e32 v187, v182, v187, vcc
	v_cmp_lt_i32_e32 vcc, v217, v186
	v_lshlrev_b32_e32 v223, 2, v187
	s_waitcnt vmcnt(0)
	v_mov_b32_e32 v155, v132
	v_cndmask_b32_e32 v217, v182, v217, vcc
	s_cselect_b64 vcc, -1, 0
	s_cmp_gt_i32 s94, 3
	v_cndmask_b32_e32 v154, 1.0, v184, vcc
	s_cselect_b64 vcc, -1, 0
	v_cndmask_b32_e32 v187, v185, v154, vcc
	v_mov_b32_e32 v154, v128
	v_mov_b32_e32 v132, v129
	v_mov_b32_e32 v128, v130
	v_mov_b32_e32 v129, v134
	v_mov_b32_e32 v134, v131
	v_pk_add_f32 v[130:131], v[154:155], v[132:133]
	v_pk_add_f32 v[128:129], v[128:129], v[134:135]
	v_lshlrev_b32_e32 v217, 2, v217
	v_pk_add_f32 v[128:129], v[130:131], v[128:129]
	v_add_f32_e32 v132, v188, v189
	v_add_f32_e32 v128, v128, v129
	ds_bpermute_b32 v129, v223, v128
	v_add_f32_e32 v133, v190, v191
	v_add_f32_e32 v134, v172, v173
	v_add_f32_e32 v135, v174, v175
	v_add_f32_e32 v154, v196, v197
	s_waitcnt lgkmcnt(0)
	v_add_f32_e32 v128, v128, v129
	ds_bpermute_b32 v129, v217, v128
	v_add_f32_e32 v155, v198, v199
	v_add_f32_e32 v172, v192, v193
	v_add_f32_e32 v173, v194, v195
	v_add_f32_e32 v130, v132, v133
	v_add_f32_e32 v131, v134, v135
	v_add_f32_e32 v132, v154, v155
	v_add_f32_e32 v133, v172, v173
	v_add_f32_e32 v130, v130, v131
	s_waitcnt lgkmcnt(0)
	v_add_f32_e32 v128, v128, v129
	v_add_f32_e32 v131, v132, v133
	ds_bpermute_b32 v132, v223, v130
	v_fmamk_f32 v128, v128, 0x3a000000, v183
	v_rsq_f32_e32 v128, v128
	v_add_f32_e32 v174, v200, v201
	v_add_f32_e32 v175, v202, v203
	s_waitcnt lgkmcnt(0)
	v_add_f32_e32 v200, v130, v132
	ds_write_b32 v251, v128
	v_mul_f32_e32 v172, v187, v128
	v_add_f32_e32 v128, v204, v205
	v_add_f32_e32 v130, v206, v207
	v_add_f32_e32 v134, v174, v175
	v_add_f32_e32 v128, v128, v130
	v_add_f32_e32 v128, v134, v128
	v_add_f32_e32 v132, v212, v213
	v_add_f32_e32 v133, v214, v215
	ds_bpermute_b32 v129, v223, v131
	ds_bpermute_b32 v130, v223, v128
	v_add_f32_e32 v132, v132, v133
	v_add_f32_e32 v133, v208, v209
	v_add_f32_e32 v134, v210, v211
	v_add_f32_e32 v133, v133, v134
	v_add_f32_e32 v132, v132, v133
	ds_bpermute_b32 v133, v223, v132
	s_waitcnt lgkmcnt(2)
	v_add_f32_e32 v198, v131, v129
	s_waitcnt lgkmcnt(1)
	v_add_f32_e32 v196, v128, v130
	v_add_f32_e32 v128, v224, v225
	v_add_f32_e32 v129, v226, v227
	v_add_f32_e32 v128, v128, v129
	v_add_f32_e32 v129, v218, v219
	v_add_f32_e32 v130, v220, v221
	v_add_f32_e32 v129, v129, v130
	v_add_f32_e32 v130, v232, v233
	v_add_f32_e32 v131, v234, v235
	s_waitcnt lgkmcnt(0)
	v_add_f32_e32 v194, v132, v133
	v_add_f32_e32 v130, v130, v131
	v_add_f32_e32 v131, v228, v229
	v_add_f32_e32 v132, v230, v231
	v_add_f32_e32 v131, v131, v132
	v_add_f32_e32 v132, v240, v241
	v_add_f32_e32 v133, v242, v243
	v_add_f32_e32 v132, v132, v133
	v_add_f32_e32 v133, v236, v237
	v_add_f32_e32 v134, v238, v239
	v_add_f32_e32 v133, v133, v134
	v_add_f32_e32 v128, v128, v129
	v_add_f32_e32 v130, v130, v131
	v_add_f32_e32 v132, v132, v133
	ds_bpermute_b32 v129, v223, v128
	ds_bpermute_b32 v131, v223, v130
	ds_bpermute_b32 v133, v223, v132
	ds_bpermute_b32 v201, v217, v200
	ds_bpermute_b32 v199, v217, v198
	s_waitcnt lgkmcnt(4)
	v_add_f32_e32 v192, v128, v129
	s_waitcnt lgkmcnt(3)
	v_add_f32_e32 v190, v130, v131
	s_waitcnt lgkmcnt(2)
	v_add_f32_e32 v188, v132, v133
	ds_bpermute_b32 v197, v217, v196
	ds_bpermute_b32 v195, v217, v194
	ds_bpermute_b32 v193, v217, v192
	ds_bpermute_b32 v191, v217, v190
	ds_bpermute_b32 v189, v217, v188
	s_waitcnt lgkmcnt(0)
	v_add_f32_e32 v250, v200, v201
	ds_write_b32 v251, v250 offset:4
	v_add_f32_e32 v249, v198, v199
	ds_write_b32 v251, v249 offset:8
	v_add_f32_e32 v248, v196, v197
	ds_write_b32 v251, v248 offset:12
	v_add_f32_e32 v250, v194, v195
	ds_write_b32 v251, v250 offset:16
	v_add_f32_e32 v249, v192, v193
	ds_write_b32 v251, v249 offset:20
	v_add_f32_e32 v248, v190, v191
	ds_write_b32 v251, v248 offset:24
	v_add_f32_e32 v250, v188, v189
	ds_write_b32 v251, v250 offset:28
	s_mov_b32 s100, 1
	s_cmp_gt_i32 s94, 15
	v_pk_mul_f32 v[74:75], v[74:75], v[172:173] op_sel_hi:[1,0]
	v_pk_mul_f32 v[72:73], v[72:73], v[172:173] op_sel_hi:[1,0]
	v_pk_mul_f32 v[82:83], v[82:83], v[172:173] op_sel_hi:[1,0]
	v_pk_mul_f32 v[80:81], v[80:81], v[172:173] op_sel_hi:[1,0]
	s_branch .Lrc3_join
; __device__ __forceinline__ unsigned cvt_pk_bf16(float lo, float hi) { f32x2 v = {lo, hi}; bf16x2_t b = __builtin_convertvector(v, bf16x2_t); return __builtin_bit_cast(unsigned, b); }
; __device__ __forceinline__ float sigmoid_f(float x) { return __builtin_amdgcn_rcpf(1.0f + __builtin_amdgcn_exp2f(-x * LOG2E)); }
;     __device__ __forceinline__ void operator()(const f32x4 (&acc)[2][2][4][2], const Unit& u, int wr, int wc, int fr, int fq) const {
;         const int row0 = u.pm * BM + wr * 64 + fr, col0 = u.pn * BM + wc * 32 + 8 * fq;
;         const bool sig = u.pn >= 16; const float sc = u.pn < 4 ? qa_scale : ((u.pn >= 8 && u.pn < 12) ? qb_scale : 1.0f);
;         float rs[2][4];
;         rows_rstd(ssq, row0, fq, sc, rs);
; #pragma unroll
;         for (int ai = 0; ai < 2; ++ai)
; #pragma unroll
;             for (int m = 0; m < 4; ++m) { const int row = row0 + ai * HALF + m * 16; const float r = rs[ai][m];
; #pragma unroll
;                 for (int bj = 0; bj < 2; ++bj) { f32x4 v0 = acc[ai][bj][m][0] * r, v1 = acc[ai][bj][m][1] * r;
;                     if (sig) {
; #pragma unroll
;                         for (int j = 0; j < 4; ++j) { v0[j] = sigmoid_f(v0[j]); v1[j] = sigmoid_f(v1[j]); } }
;                     u32x4 w; w.x = cvt_pk_bf16(v0[0], v0[1]); w.y = cvt_pk_bf16(v0[2], v0[3]); w.z = cvt_pk_bf16(v1[0], v1[1]); w.w = cvt_pk_bf16(v1[2], v1[3]);
;                     *(u32x4*)(O + (size_t)row * ldo + col0 + bj * HALF) = w; } }
.Lrc3_fast:
	v_lshrrev_b32_e32 v251, 6, v222
	v_and_b32_e32 v250, 15, v222
	v_lshl_or_b32 v251, v251, 4, v250
	v_lshlrev_b32_e32 v251, 5, v251
	v_add_u32_e32 v251, 0x20000, v251
	ds_read_b32 v249, v251
	ds_read_b32 v200, v251 offset:4
	ds_read_b32 v198, v251 offset:8
	ds_read_b32 v196, v251 offset:12
	ds_read_b32 v194, v251 offset:16
	ds_read_b32 v192, v251 offset:20
	ds_read_b32 v190, v251 offset:24
	ds_read_b32 v188, v251 offset:28
	v_mov_b32_e32 v201, 0
	v_mov_b32_e32 v199, 0
	v_mov_b32_e32 v197, 0
	v_mov_b32_e32 v195, 0
	v_mov_b32_e32 v193, 0
	v_mov_b32_e32 v191, 0
	v_mov_b32_e32 v189, 0
	s_waitcnt lgkmcnt(0)
	v_lshl_add_u32 v170, s46, 8, v176
	v_ashrrev_i32_e32 v171, 31, v170
	v_lshlrev_b64 v[128:129], 7, v[170:171]
	v_lshl_add_u64 v[132:133], v[144:145], 0, v[128:129]
	s_nop 0
	v_or_b32_e32 v168, 16, v170
	v_ashrrev_i32_e32 v169, 31, v168
	v_lshlrev_b64 v[154:155], 7, v[168:169]
	v_or_b32_e32 v166, 32, v170
	v_lshl_add_u64 v[154:155], v[144:145], 0, v[154:155]
	v_ashrrev_i32_e32 v167, 31, v166
	v_lshlrev_b64 v[154:155], 7, v[166:167]
	v_lshl_add_u64 v[154:155], v[144:145], 0, v[154:155]
	v_or_b32_e32 v164, 48, v170
	v_ashrrev_i32_e32 v165, 31, v164
	v_lshlrev_b64 v[154:155], 7, v[164:165]
	v_add_u32_e32 v162, 0x80, v170
	v_lshl_add_u64 v[154:155], v[144:145], 0, v[154:155]
	v_ashrrev_i32_e32 v163, 31, v162
	v_lshlrev_b64 v[154:155], 7, v[162:163]
	v_lshl_add_u64 v[154:155], v[144:145], 0, v[154:155]
	v_add_u32_e32 v160, 0x90, v170
	v_and_b32_e32 v154, 64, v182
	v_ashrrev_i32_e32 v161, 31, v160
	v_add_u32_e32 v158, 0xa0, v170
	v_add_u32_e32 v186, 64, v154
	v_lshlrev_b64 v[154:155], 7, v[160:161]
	v_lshl_add_u64 v[154:155], v[144:145], 0, v[154:155]
	v_ashrrev_i32_e32 v159, 31, v158
	v_add_u32_e32 v156, 0xb0, v170
	v_lshlrev_b64 v[154:155], 7, v[158:159]
	v_ashrrev_i32_e32 v157, 31, v156
	v_lshl_add_u64 v[154:155], v[144:145], 0, v[154:155]
	v_lshlrev_b64 v[154:155], 7, v[156:157]
	v_lshl_add_u64 v[154:155], v[144:145], 0, v[154:155]
	s_cmp_lt_i32 s94, 16
	v_xor_b32_e32 v187, 16, v182
	v_xor_b32_e32 v217, 32, v182
	s_cselect_b64 s[96:97], -1, 0
	s_and_b32 s10, s94, 0x7ffffffc
	v_cmp_lt_i32_e32 vcc, v187, v186
	s_cmp_eq_u32 s10, 8
	s_mov_b64 s[10:11], -1
	v_cndmask_b32_e32 v187, v182, v187, vcc
	v_cmp_lt_i32_e32 vcc, v217, v186
	v_lshlrev_b32_e32 v223, 2, v187
	v_cndmask_b32_e32 v217, v182, v217, vcc
	s_cselect_b64 vcc, -1, 0
	s_cmp_gt_i32 s94, 3
	v_cndmask_b32_e32 v154, 1.0, v184, vcc
	s_cselect_b64 vcc, -1, 0
	v_cndmask_b32_e32 v187, v185, v154, vcc
	v_lshlrev_b32_e32 v217, 2, v217
	s_waitcnt lgkmcnt(0)
	s_waitcnt lgkmcnt(0)
	s_waitcnt lgkmcnt(0)
	v_mov_b32_e32 v128, v249
	v_mul_f32_e32 v172, v187, v128
	s_waitcnt lgkmcnt(2)
	s_waitcnt lgkmcnt(1)
	s_waitcnt lgkmcnt(0)
	s_waitcnt lgkmcnt(4)
	s_waitcnt lgkmcnt(3)
	s_waitcnt lgkmcnt(2)
	s_cmp_gt_i32 s94, 15
	v_pk_mul_f32 v[74:75], v[74:75], v[172:173] op_sel_hi:[1,0]
	v_pk_mul_f32 v[72:73], v[72:73], v[172:173] op_sel_hi:[1,0]
	v_pk_mul_f32 v[82:83], v[82:83], v[172:173] op_sel_hi:[1,0]
	v_pk_mul_f32 v[80:81], v[80:81], v[172:173] op_sel_hi:[1,0]
.Lrc3_join:
	s_cbranch_scc1 .LBB0_408
	v_mov_b64_e32 v[134:135], v[82:83]
	v_mov_b64_e32 v[130:131], v[74:75]
	s_mov_b64 s[10:11], 0
	v_mov_b64_e32 v[132:133], v[80:81]
	v_mov_b64_e32 v[128:129], v[72:73]
